# code placement: the five K-loop heads aligned to 64 bytes (padding is unreachable behind the peel's branch); otherwise the best version
# speedup vs baseline: 1.0084x; 1.0084x over previous
; #define PG8_STAGE(bufoff, gbase, voff) do { _Pragma("unroll") for (int _i = 0; _i < 2; ++_i) \
;         __builtin_amdgcn_global_load_lds((const unsigned*)((const char*)(gbase) + (voff)[_i]), (PG8_LAS unsigned*)(lds + (bufoff) + ldsw + _i * 8192), 16, 0, 0); } while (0)
; #define PG8_LDA(dst, b, h) do { _Pragma("unroll") for (int m = 0; m < 4; ++m) _Pragma("unroll") for (int k = 0; k < 2; ++k) dst[m][k] = *(const PG8_LAS bf16x8*)(lds + PG8_SA(b, h) + aoff + m * 2048 + k * 1024); } while (0)
; #define PG8_LDB(dst, b, h) do { _Pragma("unroll") for (int n = 0; n < 2; ++n) _Pragma("unroll") for (int k = 0; k < 2; ++k) dst[n][k] = *(const PG8_LAS bf16x8*)(lds + PG8_SB(b, h) + boff + n * 2048 + k * 1024); } while (0)
; #define PG8_WAIT_V(n) asm volatile("s_waitcnt vmcnt(" #n ")" ::: "memory")
; #define PG8_WAIT_L(n) asm volatile("s_waitcnt lgkmcnt(" #n ")" ::: "memory")
; #define PG8_BAR __builtin_amdgcn_s_barrier()
; template <class Epi, class Sched, bool ALIGN_EPI = false, bool SP2 = false, bool F8 = false>
; __device__ __forceinline__ void gemm_phase(PG8_LAS unsigned char* lds, const int K, const Sched& S, const Epi& E, const int wave) {
;     ...
;             const bool last = (t == nt - 2);
;             const char* a1 = cA + (size_t)(t + 1) * kstep;
;             const char* a2 = last ? nA : cA + (size_t)(t + 2) * kstep; const char* b2 = last ? nB : cB + (size_t)(t + 2) * kstep;
;             const char* a3 = a2 + kstep; const char* b3 = b2 + kstep;
;             asm volatile("" : "+s"(a1), "+s"(a2), "+s"(b2), "+s"(a3), "+s"(b3));
;             if (last && has_next) S.a_ready(nxt);
;             if constexpr (Epi::KHOOK) { if (cur.prob == 2 ? (t == 16) : (t == 32 || t == 48)) { if (wr == 0) PG8_BAR;
;                 E.khook(acc, cur, (cur.prob == 2 || t == 48) ? 1 : 0, wr, wc, fr, fq); if (wr == 1) PG8_BAR; } }
;             if constexpr (SP2) {
;             PG8_LDB(B0, 0, 0); PG8_LDB(B1, 0, 1); PG8_SCHED; PG8_LDA(At, 0, 0); PG8_STAGE(PG8_SA(1, 1), a1 + hstep, voffA);
;             PG8_WAIT_V(8); PG8_WAIT_L(0); PG8_BAR; PG8_MMA(0, 0, At, B0); PG8_MMA(0, 1, At, B1); PG8_BAR; PG8_SCHED;
;             PG8_LDA(At, 0, 1); PG8_STAGE(PG8_SB(0, 0), b2, voffB); PG8_STAGE(PG8_SB(0, 1), b2 + hstep, voffB); PG8_STAGE(PG8_SA(0, 0), a2, voffA);
;             PG8_WAIT_V(8); PG8_WAIT_L(0); PG8_BAR; PG8_MMA(1, 0, At, B0); PG8_MMA(1, 1, At, B1); PG8_BAR; PG8_SCHED;
.Lpeel_k186:
	s_add_u32 s6, s14, s0
	s_addc_u32 s7, s15, s1
	s_add_u32 s64, s6, 0xffffff80
	s_addc_u32 s65, s7, -1
	s_add_u32 s76, s36, s0
	s_addc_u32 s77, s37, s1
	s_cmp_eq_u32 vcc_lo, 60
	s_cselect_b32 s94, s85, s6
	s_cselect_b32 s95, s83, s7
	s_cselect_b32 s7, s96, s77
	s_cselect_b32 s6, s97, s76
	s_add_u32 s78, s94, 0x80
	s_addc_u32 s79, s95, 0
	s_add_u32 s76, s6, 0x80
	s_addc_u32 s77, s7, 0
	v_add_u32_e32 v140, s47, v245
	v_add_u32_e32 v156, s41, v245
	ds_read_b128 v[128:131], v140
	ds_read_b128 v[132:135], v140 offset:1024
	ds_read_b128 v[136:139], v140 offset:2048
	ds_read_b128 v[140:143], v140 offset:3072
	ds_read_b128 v[144:147], v156
	ds_read_b128 v[148:151], v156 offset:1024
	ds_read_b128 v[152:155], v156 offset:2048
	ds_read_b128 v[156:159], v156 offset:3072
	s_add_u32 s64, s64, 0x100000
	s_addc_u32 s65, s65, 0
	s_add_i32 m0, s13, 0xc000
	ds_read_b128 v[160:163], v248
	ds_read_b128 v[164:167], v248 offset:1024
	ds_read_b128 v[168:171], v248 offset:2048
	ds_read_b128 v[172:175], v248 offset:3072
	ds_read_b128 v[176:179], v248 offset:4096
	ds_read_b128 v[180:183], v248 offset:5120
	ds_read_b128 v[184:187], v248 offset:6144
	ds_read_b128 v[188:191], v248 offset:7168
	global_load_lds_dwordx4 v192, s[64:65]
	s_add_i32 m0, s13, 0xe000
	s_nop 0
	global_load_lds_dwordx4 v196, s[64:65]
	s_waitcnt vmcnt(8)
	s_waitcnt lgkmcnt(0)
	s_setprio 1
	s_barrier
	v_mfma_f32_16x16x32_bf16 v[124:127], v[128:131], v[160:163], 0
	v_mfma_f32_16x16x32_bf16 v[120:123], v[136:139], v[160:163], 0
	v_mfma_f32_16x16x32_bf16 v[116:119], v[128:131], v[168:171], 0
	v_mfma_f32_16x16x32_bf16 v[112:115], v[136:139], v[168:171], 0
	v_mfma_f32_16x16x32_bf16 v[108:111], v[128:131], v[176:179], 0
	v_mfma_f32_16x16x32_bf16 v[104:107], v[136:139], v[176:179], 0
	v_mfma_f32_16x16x32_bf16 v[100:103], v[128:131], v[184:187], 0
	v_mfma_f32_16x16x32_bf16 v[96:99], v[136:139], v[184:187], 0
	v_mfma_f32_16x16x32_bf16 v[124:127], v[132:135], v[164:167], v[124:127]
	v_mfma_f32_16x16x32_bf16 v[120:123], v[140:143], v[164:167], v[120:123]
	v_mfma_f32_16x16x32_bf16 v[116:119], v[132:135], v[172:175], v[116:119]
	v_mfma_f32_16x16x32_bf16 v[112:115], v[140:143], v[172:175], v[112:115]
	v_mfma_f32_16x16x32_bf16 v[108:111], v[132:135], v[180:183], v[108:111]
	v_mfma_f32_16x16x32_bf16 v[104:107], v[140:143], v[180:183], v[104:107]
	v_mfma_f32_16x16x32_bf16 v[100:103], v[132:135], v[188:191], v[100:103]
	v_mfma_f32_16x16x32_bf16 v[96:99], v[140:143], v[188:191], v[96:99]
	v_mfma_f32_16x16x32_bf16 v[92:95], v[144:147], v[160:163], 0
	v_mfma_f32_16x16x32_bf16 v[88:91], v[152:155], v[160:163], 0
	v_mfma_f32_16x16x32_bf16 v[84:87], v[144:147], v[168:171], 0
	v_mfma_f32_16x16x32_bf16 v[80:83], v[152:155], v[168:171], 0
	v_mfma_f32_16x16x32_bf16 v[76:79], v[144:147], v[176:179], 0
	v_mfma_f32_16x16x32_bf16 v[72:75], v[152:155], v[176:179], 0
	v_mfma_f32_16x16x32_bf16 v[68:71], v[144:147], v[184:187], 0
	v_mfma_f32_16x16x32_bf16 v[64:67], v[152:155], v[184:187], 0
	v_mfma_f32_16x16x32_bf16 v[92:95], v[148:151], v[164:167], v[92:95]
	v_mfma_f32_16x16x32_bf16 v[88:91], v[156:159], v[164:167], v[88:91]
	v_mfma_f32_16x16x32_bf16 v[84:87], v[148:151], v[172:175], v[84:87]
	v_mfma_f32_16x16x32_bf16 v[80:83], v[156:159], v[172:175], v[80:83]
	v_mfma_f32_16x16x32_bf16 v[76:79], v[148:151], v[180:183], v[76:79]
	v_mfma_f32_16x16x32_bf16 v[72:75], v[156:159], v[180:183], v[72:75]
	v_mfma_f32_16x16x32_bf16 v[68:71], v[148:151], v[188:191], v[68:71]
	v_mfma_f32_16x16x32_bf16 v[64:67], v[156:159], v[188:191], v[64:67]
	s_barrier
	s_setprio 0
	s_add_i32 s64, s47, s74
	s_mov_b32 m0, s64
	ds_read_b128 v[160:163], v248 offset:16384
	ds_read_b128 v[164:167], v248 offset:17408
	ds_read_b128 v[168:171], v248 offset:18432
	ds_read_b128 v[172:175], v248 offset:19456
	ds_read_b128 v[176:179], v248 offset:20480
	ds_read_b128 v[180:183], v248 offset:21504
	ds_read_b128 v[184:187], v248 offset:22528
	ds_read_b128 v[188:191], v248 offset:23552
	global_load_lds_dwordx4 v194, s[6:7]
	s_add_i32 m0, s64, 0x2000
	s_nop 0
	global_load_lds_dwordx4 v198, s[6:7]
	s_add_u32 s6, s6, 0x100000
	s_addc_u32 s7, s7, 0
	s_add_i32 s64, s41, s74
	s_mov_b32 m0, s64
	s_nop 0
	global_load_lds_dwordx4 v194, s[6:7]
	s_add_i32 m0, s64, 0x2000
	s_nop 0
	global_load_lds_dwordx4 v198, s[6:7]
	s_mov_b32 m0, s13
	s_nop 0
	global_load_lds_dwordx4 v192, s[94:95]
	s_mov_b32 m0, s51
	s_nop 0
	global_load_lds_dwordx4 v196, s[94:95]
	s_waitcnt vmcnt(8)
	s_waitcnt lgkmcnt(0)
	s_setprio 1
	s_barrier
	v_mfma_f32_16x16x32_bf16 v[60:63], v[128:131], v[160:163], 0
	v_mfma_f32_16x16x32_bf16 v[56:59], v[136:139], v[160:163], 0
	v_mfma_f32_16x16x32_bf16 v[52:55], v[128:131], v[168:171], 0
	v_mfma_f32_16x16x32_bf16 v[48:51], v[136:139], v[168:171], 0
	v_mfma_f32_16x16x32_bf16 v[44:47], v[128:131], v[176:179], 0
	v_mfma_f32_16x16x32_bf16 v[40:43], v[136:139], v[176:179], 0
	v_mfma_f32_16x16x32_bf16 v[36:39], v[128:131], v[184:187], 0
	v_mfma_f32_16x16x32_bf16 v[32:35], v[136:139], v[184:187], 0
	v_mfma_f32_16x16x32_bf16 v[60:63], v[132:135], v[164:167], v[60:63]
	v_mfma_f32_16x16x32_bf16 v[56:59], v[140:143], v[164:167], v[56:59]
	v_mfma_f32_16x16x32_bf16 v[52:55], v[132:135], v[172:175], v[52:55]
	v_mfma_f32_16x16x32_bf16 v[48:51], v[140:143], v[172:175], v[48:51]
	v_mfma_f32_16x16x32_bf16 v[44:47], v[132:135], v[180:183], v[44:47]
	v_mfma_f32_16x16x32_bf16 v[40:43], v[140:143], v[180:183], v[40:43]
	v_mfma_f32_16x16x32_bf16 v[36:39], v[132:135], v[188:191], v[36:39]
	v_mfma_f32_16x16x32_bf16 v[32:35], v[140:143], v[188:191], v[32:35]
	v_mfma_f32_16x16x32_bf16 v[28:31], v[144:147], v[160:163], 0
	v_mfma_f32_16x16x32_bf16 v[24:27], v[152:155], v[160:163], 0
	v_mfma_f32_16x16x32_bf16 v[20:23], v[144:147], v[168:171], 0
	v_mfma_f32_16x16x32_bf16 v[16:19], v[152:155], v[168:171], 0
	v_mfma_f32_16x16x32_bf16 v[12:15], v[144:147], v[176:179], 0
	v_mfma_f32_16x16x32_bf16 v[8:11], v[152:155], v[176:179], 0
	v_mfma_f32_16x16x32_bf16 v[4:7], v[144:147], v[184:187], 0
	v_mfma_f32_16x16x32_bf16 v[0:3], v[152:155], v[184:187], 0
	v_mfma_f32_16x16x32_bf16 v[28:31], v[148:151], v[164:167], v[28:31]
	v_mfma_f32_16x16x32_bf16 v[24:27], v[156:159], v[164:167], v[24:27]
	v_mfma_f32_16x16x32_bf16 v[20:23], v[148:151], v[172:175], v[20:23]
	v_mfma_f32_16x16x32_bf16 v[16:19], v[156:159], v[172:175], v[16:19]
	v_mfma_f32_16x16x32_bf16 v[12:15], v[148:151], v[180:183], v[12:15]
	v_mfma_f32_16x16x32_bf16 v[8:11], v[156:159], v[180:183], v[8:11]
	v_mfma_f32_16x16x32_bf16 v[4:7], v[148:151], v[188:191], v[4:7]
	v_mfma_f32_16x16x32_bf16 v[0:3], v[156:159], v[188:191], v[0:3]
	s_barrier
	s_branch .Lmid_k186
	.p2align	6

; #define PG8_STAGE(bufoff, gbase, voff) do { _Pragma("unroll") for (int _i = 0; _i < 2; ++_i) \
;         __builtin_amdgcn_global_load_lds((const unsigned*)((const char*)(gbase) + (voff)[_i]), (PG8_LAS unsigned*)(lds + (bufoff) + ldsw + _i * 8192), 16, 0, 0); } while (0)
; #define PG8_LDA(dst, b, h) do { _Pragma("unroll") for (int m = 0; m < 4; ++m) _Pragma("unroll") for (int k = 0; k < 2; ++k) dst[m][k] = *(const PG8_LAS bf16x8*)(lds + PG8_SA(b, h) + aoff + m * 2048 + k * 1024); } while (0)
; #define PG8_LDB(dst, b, h) do { _Pragma("unroll") for (int n = 0; n < 2; ++n) _Pragma("unroll") for (int k = 0; k < 2; ++k) dst[n][k] = *(const PG8_LAS bf16x8*)(lds + PG8_SB(b, h) + boff + n * 2048 + k * 1024); } while (0)
; #define PG8_WAIT_V(n) asm volatile("s_waitcnt vmcnt(" #n ")" ::: "memory")
; #define PG8_WAIT_L(n) asm volatile("s_waitcnt lgkmcnt(" #n ")" ::: "memory")
; #define PG8_BAR __builtin_amdgcn_s_barrier()
; template <class Epi, class Sched, bool ALIGN_EPI = false, bool SP2 = false, bool F8 = false>
; __device__ __forceinline__ void gemm_phase(PG8_LAS unsigned char* lds, const int K, const Sched& S, const Epi& E, const int wave) {
;     ...
;             const bool last = (t == nt - 2);
;             const char* a1 = cA + (size_t)(t + 1) * kstep;
;             const char* a2 = last ? nA : cA + (size_t)(t + 2) * kstep; const char* b2 = last ? nB : cB + (size_t)(t + 2) * kstep;
;             const char* a3 = a2 + kstep; const char* b3 = b2 + kstep;
;             asm volatile("" : "+s"(a1), "+s"(a2), "+s"(b2), "+s"(a3), "+s"(b3));
;             if (last && has_next) S.a_ready(nxt);
;             if constexpr (Epi::KHOOK) { if (cur.prob == 2 ? (t == 16) : (t == 32 || t == 48)) { if (wr == 0) PG8_BAR;
;                 E.khook(acc, cur, (cur.prob == 2 || t == 48) ? 1 : 0, wr, wc, fr, fq); if (wr == 1) PG8_BAR; } }
;             if constexpr (SP2) {
;             PG8_LDB(B0, 0, 0); PG8_LDB(B1, 0, 1); PG8_SCHED; PG8_LDA(At, 0, 0); PG8_STAGE(PG8_SA(1, 1), a1 + hstep, voffA);
;             PG8_WAIT_V(8); PG8_WAIT_L(0); PG8_BAR; PG8_MMA(0, 0, At, B0); PG8_MMA(0, 1, At, B1); PG8_BAR; PG8_SCHED;
;             PG8_LDA(At, 0, 1); PG8_STAGE(PG8_SB(0, 0), b2, voffB); PG8_STAGE(PG8_SB(0, 1), b2 + hstep, voffB); PG8_STAGE(PG8_SA(0, 0), a2, voffA);
;             PG8_WAIT_V(8); PG8_WAIT_L(0); PG8_BAR; PG8_MMA(1, 0, At, B0); PG8_MMA(1, 1, At, B1); PG8_BAR; PG8_SCHED;
.Lpeel_k248:
	s_add_u32 s6, s10, s94
	s_addc_u32 s7, s11, s95
	s_add_u32 s36, s6, 0xffffff80
	s_addc_u32 s37, s7, -1
	s_add_u32 s78, s12, s94
	s_addc_u32 s79, s13, s95
	s_cmp_eq_u32 s38, 28
	s_cselect_b32 s76, s90, s6
	s_cselect_b32 s77, s91, s7
	s_cselect_b32 s7, s93, s79
	s_cselect_b32 s6, s92, s78
	s_add_u32 s96, s76, 0x80
	s_addc_u32 s97, s77, 0
	s_add_u32 s78, s6, 0x80
	s_addc_u32 s79, s7, 0
	v_add_u32_e32 v128, s49, v163
	ds_read_b128 v[140:143], v128
	ds_read_b128 v[144:147], v128 offset:1024
	ds_read_b128 v[148:151], v128 offset:2048
	ds_read_b128 v[152:155], v128 offset:3072
	v_add_u32_e32 v128, s50, v163
	ds_read_b128 v[168:171], v128
	ds_read_b128 v[172:175], v128 offset:1024
	ds_read_b128 v[176:179], v128 offset:2048
	ds_read_b128 v[180:183], v128 offset:3072
	s_add_u32 s36, s36, 0x100000
	s_addc_u32 s37, s37, 0
	s_add_i32 m0, s42, 0xc000
	ds_read_b128 v[184:187], v165
	ds_read_b128 v[188:191], v165 offset:1024
	ds_read_b128 v[192:195], v165 offset:2048
	ds_read_b128 v[196:199], v165 offset:3072
	ds_read_b128 v[200:203], v165 offset:4096
	ds_read_b128 v[204:207], v165 offset:5120
	ds_read_b128 v[208:211], v165 offset:6144
	ds_read_b128 v[212:215], v165 offset:7168
	global_load_lds_dwordx4 v134, s[36:37]
	s_add_i32 m0, s42, 0xe000
	s_nop 0
	global_load_lds_dwordx4 v160, s[36:37]
	s_waitcnt vmcnt(8)
	s_waitcnt lgkmcnt(0)
	s_setprio 1
	s_barrier
	v_mfma_scale_f32_16x16x128_f8f6f4 v[124:127], v[140:147], v[184:191], 0, v166, v166 op_sel_hi:[0, 0, 0]
	v_mfma_scale_f32_16x16x128_f8f6f4 v[120:123], v[148:155], v[184:191], 0, v166, v166 op_sel_hi:[0, 0, 0]
	v_mfma_scale_f32_16x16x128_f8f6f4 v[116:119], v[140:147], v[192:199], 0, v166, v166 op_sel_hi:[0, 0, 0]
	v_mfma_scale_f32_16x16x128_f8f6f4 v[112:115], v[148:155], v[192:199], 0, v166, v166 op_sel_hi:[0, 0, 0]
	v_mfma_scale_f32_16x16x128_f8f6f4 v[108:111], v[140:147], v[200:207], 0, v166, v166 op_sel_hi:[0, 0, 0]
	v_mfma_scale_f32_16x16x128_f8f6f4 v[104:107], v[148:155], v[200:207], 0, v166, v166 op_sel_hi:[0, 0, 0]
	v_mfma_scale_f32_16x16x128_f8f6f4 v[100:103], v[140:147], v[208:215], 0, v166, v166 op_sel_hi:[0, 0, 0]
	v_mfma_scale_f32_16x16x128_f8f6f4 v[96:99], v[148:155], v[208:215], 0, v166, v166 op_sel_hi:[0, 0, 0]
	v_mfma_scale_f32_16x16x128_f8f6f4 v[156:159], v[168:175], v[184:191], 0, v166, v166 op_sel_hi:[0, 0, 0]
	v_mfma_scale_f32_16x16x128_f8f6f4 v[184:187], v[176:183], v[184:191], 0, v166, v166 op_sel_hi:[0, 0, 0]
	v_mfma_scale_f32_16x16x128_f8f6f4 v[188:191], v[168:175], v[192:199], 0, v166, v166 op_sel_hi:[0, 0, 0]
	v_mfma_scale_f32_16x16x128_f8f6f4 v[192:195], v[176:183], v[192:199], 0, v166, v166 op_sel_hi:[0, 0, 0]
	v_mfma_scale_f32_16x16x128_f8f6f4 v[196:199], v[168:175], v[200:207], 0, v166, v166 op_sel_hi:[0, 0, 0]
	v_mfma_scale_f32_16x16x128_f8f6f4 v[200:203], v[176:183], v[200:207], 0, v166, v166 op_sel_hi:[0, 0, 0]
	v_mfma_scale_f32_16x16x128_f8f6f4 v[204:207], v[168:175], v[208:215], 0, v166, v166 op_sel_hi:[0, 0, 0]
	v_mfma_scale_f32_16x16x128_f8f6f4 v[208:211], v[176:183], v[208:215], 0, v166, v166 op_sel_hi:[0, 0, 0]
	s_barrier
	s_setprio 0
	s_add_i32 s36, s49, s74
	s_mov_b32 m0, s36
	s_nop 1
	ds_read_b128 v[64:67], v165 offset:16384
	ds_read_b128 v[68:71], v165 offset:17408
	ds_read_b128 v[72:75], v165 offset:18432
	ds_read_b128 v[76:79], v165 offset:19456
	ds_read_b128 v[80:83], v165 offset:20480
	ds_read_b128 v[84:87], v165 offset:21504
	ds_read_b128 v[88:91], v165 offset:22528
	ds_read_b128 v[92:95], v165 offset:23552
	global_load_lds_dwordx4 v132, s[6:7]
	s_add_i32 m0, s36, 0x2000
	s_nop 0
	global_load_lds_dwordx4 v252, s[6:7]
	s_add_u32 s6, s6, 0x100000
	s_addc_u32 s7, s7, 0
	s_add_i32 s36, s50, s74
	s_mov_b32 m0, s36
	s_nop 0
	global_load_lds_dwordx4 v132, s[6:7]
	s_add_i32 m0, s36, 0x2000
	s_nop 0
	global_load_lds_dwordx4 v252, s[6:7]
	s_mov_b32 m0, s42
	s_nop 0
	global_load_lds_dwordx4 v134, s[76:77]
	s_mov_b32 m0, s43
	s_nop 0
	global_load_lds_dwordx4 v160, s[76:77]
	s_waitcnt vmcnt(8)
	s_waitcnt lgkmcnt(0)
	s_setprio 1
	s_barrier
	v_mfma_scale_f32_16x16x128_f8f6f4 v[60:63], v[140:147], v[64:71], 0, v166, v166 op_sel_hi:[0, 0, 0]
	v_mfma_scale_f32_16x16x128_f8f6f4 v[56:59], v[148:155], v[64:71], 0, v166, v166 op_sel_hi:[0, 0, 0]
	v_mfma_scale_f32_16x16x128_f8f6f4 v[52:55], v[140:147], v[72:79], 0, v166, v166 op_sel_hi:[0, 0, 0]
	v_mfma_scale_f32_16x16x128_f8f6f4 v[48:51], v[148:155], v[72:79], 0, v166, v166 op_sel_hi:[0, 0, 0]
	v_mfma_scale_f32_16x16x128_f8f6f4 v[212:215], v[140:147], v[80:87], 0, v166, v166 op_sel_hi:[0, 0, 0]
	v_mfma_scale_f32_16x16x128_f8f6f4 v[216:219], v[148:155], v[80:87], 0, v166, v166 op_sel_hi:[0, 0, 0]
	v_mfma_scale_f32_16x16x128_f8f6f4 v[220:223], v[140:147], v[88:95], 0, v166, v166 op_sel_hi:[0, 0, 0]
	v_mfma_scale_f32_16x16x128_f8f6f4 v[224:227], v[148:155], v[88:95], 0, v166, v166 op_sel_hi:[0, 0, 0]
	v_mfma_scale_f32_16x16x128_f8f6f4 v[228:231], v[168:175], v[64:71], 0, v166, v166 op_sel_hi:[0, 0, 0]
	v_mfma_scale_f32_16x16x128_f8f6f4 v[236:239], v[176:183], v[64:71], 0, v166, v166 op_sel_hi:[0, 0, 0]
	v_mfma_scale_f32_16x16x128_f8f6f4 v[244:247], v[168:175], v[72:79], 0, v166, v166 op_sel_hi:[0, 0, 0]
	v_mfma_scale_f32_16x16x128_f8f6f4 v[248:251], v[176:183], v[72:79], 0, v166, v166 op_sel_hi:[0, 0, 0]
	v_mfma_scale_f32_16x16x128_f8f6f4 v[232:235], v[168:175], v[80:87], 0, v166, v166 op_sel_hi:[0, 0, 0]
	v_mfma_scale_f32_16x16x128_f8f6f4 v[240:243], v[176:183], v[80:87], 0, v166, v166 op_sel_hi:[0, 0, 0]
	v_mfma_scale_f32_16x16x128_f8f6f4 v[136:139], v[168:175], v[88:95], 0, v166, v166 op_sel_hi:[0, 0, 0]
	v_mfma_scale_f32_16x16x128_f8f6f4 v[128:131], v[176:183], v[88:95], 0, v166, v166 op_sel_hi:[0, 0, 0]
	s_barrier
	s_branch .Lmid_k248
	.p2align	6

; #define PG8_STAGE(bufoff, gbase, voff) do { _Pragma("unroll") for (int _i = 0; _i < 2; ++_i) \
;         __builtin_amdgcn_global_load_lds((const unsigned*)((const char*)(gbase) + (voff)[_i]), (PG8_LAS unsigned*)(lds + (bufoff) + ldsw + _i * 8192), 16, 0, 0); } while (0)
; #define PG8_LDA(dst, b, h) do { _Pragma("unroll") for (int m = 0; m < 4; ++m) _Pragma("unroll") for (int k = 0; k < 2; ++k) dst[m][k] = *(const PG8_LAS bf16x8*)(lds + PG8_SA(b, h) + aoff + m * 2048 + k * 1024); } while (0)
; #define PG8_LDB(dst, b, h) do { _Pragma("unroll") for (int n = 0; n < 2; ++n) _Pragma("unroll") for (int k = 0; k < 2; ++k) dst[n][k] = *(const PG8_LAS bf16x8*)(lds + PG8_SB(b, h) + boff + n * 2048 + k * 1024); } while (0)
; #define PG8_WAIT_V(n) asm volatile("s_waitcnt vmcnt(" #n ")" ::: "memory")
; #define PG8_WAIT_L(n) asm volatile("s_waitcnt lgkmcnt(" #n ")" ::: "memory")
; #define PG8_BAR __builtin_amdgcn_s_barrier()
; template <class Epi, class Sched, bool ALIGN_EPI = false, bool SP2 = false, bool F8 = false>
; __device__ __forceinline__ void gemm_phase(PG8_LAS unsigned char* lds, const int K, const Sched& S, const Epi& E, const int wave) {
;     ...
;             const bool last = (t == nt - 2);
;             const char* a1 = cA + (size_t)(t + 1) * kstep;
;             const char* a2 = last ? nA : cA + (size_t)(t + 2) * kstep; const char* b2 = last ? nB : cB + (size_t)(t + 2) * kstep;
;             const char* a3 = a2 + kstep; const char* b3 = b2 + kstep;
;             asm volatile("" : "+s"(a1), "+s"(a2), "+s"(b2), "+s"(a3), "+s"(b3));
;             if (last && has_next) S.a_ready(nxt);
;             if constexpr (Epi::KHOOK) { if (cur.prob == 2 ? (t == 16) : (t == 32 || t == 48)) { if (wr == 0) PG8_BAR;
;                 E.khook(acc, cur, (cur.prob == 2 || t == 48) ? 1 : 0, wr, wc, fr, fq); if (wr == 1) PG8_BAR; } }
;             if constexpr (SP2) {
;             PG8_LDB(B0, 0, 0); PG8_LDB(B1, 0, 1); PG8_SCHED; PG8_LDA(At, 0, 0); PG8_STAGE(PG8_SA(1, 1), a1 + hstep, voffA);
;             PG8_WAIT_V(8); PG8_WAIT_L(0); PG8_BAR; PG8_MMA(0, 0, At, B0); PG8_MMA(0, 1, At, B1); PG8_BAR; PG8_SCHED;
;             PG8_LDA(At, 0, 1); PG8_STAGE(PG8_SB(0, 0), b2, voffB); PG8_STAGE(PG8_SB(0, 1), b2 + hstep, voffB); PG8_STAGE(PG8_SA(0, 0), a2, voffA);
;             PG8_WAIT_V(8); PG8_WAIT_L(0); PG8_BAR; PG8_MMA(1, 0, At, B0); PG8_MMA(1, 1, At, B1); PG8_BAR; PG8_SCHED;
.Lpeel_k966:
	s_add_i32 s90, s8, 2
	s_cmp_eq_u32 s85, s8
	s_cselect_b32 s42, s31, s86
	s_cselect_b32 s43, s25, s87
	s_cselect_b32 s57, s83, s89
	s_cselect_b32 s56, s84, s88
	s_add_u32 s8, s42, 0x80
	s_addc_u32 s9, s43, 0
	s_add_u32 s40, s56, 0x80
	s_addc_u32 s41, s57, 0
	s_mov_b64 s[92:93], s[6:7]
	v_add_u32_e32 v1, s77, v168
	ds_read_b128 v[132:135], v1
	ds_read_b128 v[136:139], v1 offset:1024
	ds_read_b128 v[156:159], v1 offset:2048
	ds_read_b128 v[160:163], v1 offset:3072
	v_add_u32_e32 v1, s78, v168
	ds_read_b128 v[172:175], v1
	ds_read_b128 v[176:179], v1 offset:1024
	ds_read_b128 v[180:183], v1 offset:2048
	ds_read_b128 v[184:187], v1 offset:3072
	s_add_u32 s92, s92, 0x100000
	s_addc_u32 s93, s93, 0
	s_add_i32 m0, s64, 0xc000
	ds_read_b128 v[188:191], v170
	ds_read_b128 v[192:195], v170 offset:1024
	ds_read_b128 v[196:199], v170 offset:2048
	ds_read_b128 v[200:203], v170 offset:3072
	ds_read_b128 v[204:207], v170 offset:4096
	ds_read_b128 v[208:211], v170 offset:5120
	ds_read_b128 v[212:215], v170 offset:6144
	ds_read_b128 v[216:219], v170 offset:7168
	global_load_lds_dwordx4 v140, s[92:93]
	s_add_i32 m0, s64, 0xe000
	s_nop 0
	global_load_lds_dwordx4 v144, s[92:93]
	s_waitcnt vmcnt(8)
	s_waitcnt lgkmcnt(0)
	s_setprio 1
	s_barrier
	v_mfma_f32_16x16x32_bf16 v[128:131], v[132:135], v[188:191], 0
	v_mfma_f32_16x16x32_bf16 v[124:127], v[156:159], v[188:191], 0
	v_mfma_f32_16x16x32_bf16 v[120:123], v[132:135], v[196:199], 0
	v_mfma_f32_16x16x32_bf16 v[116:119], v[156:159], v[196:199], 0
	v_mfma_f32_16x16x32_bf16 v[112:115], v[132:135], v[204:207], 0
	v_mfma_f32_16x16x32_bf16 v[108:111], v[156:159], v[204:207], 0
	v_mfma_f32_16x16x32_bf16 v[104:107], v[132:135], v[212:215], 0
	v_mfma_f32_16x16x32_bf16 v[100:103], v[156:159], v[212:215], 0
	v_mfma_f32_16x16x32_bf16 v[128:131], v[136:139], v[192:195], v[128:131]
	v_mfma_f32_16x16x32_bf16 v[124:127], v[160:163], v[192:195], v[124:127]
	v_mfma_f32_16x16x32_bf16 v[120:123], v[136:139], v[200:203], v[120:123]
	v_mfma_f32_16x16x32_bf16 v[116:119], v[160:163], v[200:203], v[116:119]
	v_mfma_f32_16x16x32_bf16 v[112:115], v[136:139], v[208:211], v[112:115]
	v_mfma_f32_16x16x32_bf16 v[108:111], v[160:163], v[208:211], v[108:111]
	v_mfma_f32_16x16x32_bf16 v[104:107], v[136:139], v[216:219], v[104:107]
	v_mfma_f32_16x16x32_bf16 v[100:103], v[160:163], v[216:219], v[100:103]
	v_mfma_f32_16x16x32_bf16 v[96:99], v[172:175], v[188:191], 0
	v_mfma_f32_16x16x32_bf16 v[92:95], v[180:183], v[188:191], 0
	v_mfma_f32_16x16x32_bf16 v[88:91], v[172:175], v[196:199], 0
	v_mfma_f32_16x16x32_bf16 v[84:87], v[180:183], v[196:199], 0
	v_mfma_f32_16x16x32_bf16 v[80:83], v[172:175], v[204:207], 0
	v_mfma_f32_16x16x32_bf16 v[76:79], v[180:183], v[204:207], 0
	v_mfma_f32_16x16x32_bf16 v[72:75], v[172:175], v[212:215], 0
	v_mfma_f32_16x16x32_bf16 v[68:71], v[180:183], v[212:215], 0
	v_mfma_f32_16x16x32_bf16 v[96:99], v[176:179], v[192:195], v[96:99]
	v_mfma_f32_16x16x32_bf16 v[92:95], v[184:187], v[192:195], v[92:95]
	v_mfma_f32_16x16x32_bf16 v[88:91], v[176:179], v[200:203], v[88:91]
	v_mfma_f32_16x16x32_bf16 v[84:87], v[184:187], v[200:203], v[84:87]
	v_mfma_f32_16x16x32_bf16 v[80:83], v[176:179], v[208:211], v[80:83]
	v_mfma_f32_16x16x32_bf16 v[76:79], v[184:187], v[208:211], v[76:79]
	v_mfma_f32_16x16x32_bf16 v[72:75], v[176:179], v[216:219], v[72:75]
	v_mfma_f32_16x16x32_bf16 v[68:71], v[184:187], v[216:219], v[68:71]
	s_barrier
	s_setprio 0
	s_add_i32 s91, s77, s63
	s_mov_b32 m0, s91
	ds_read_b128 v[188:191], v170 offset:16384
	ds_read_b128 v[192:195], v170 offset:17408
	ds_read_b128 v[196:199], v170 offset:18432
	ds_read_b128 v[200:203], v170 offset:19456
	ds_read_b128 v[204:207], v170 offset:20480
	ds_read_b128 v[208:211], v170 offset:21504
	ds_read_b128 v[212:215], v170 offset:22528
	ds_read_b128 v[216:219], v170 offset:23552
	global_load_lds_dwordx4 v142, s[56:57]
	s_add_i32 m0, s91, 0x2000
	s_nop 0
	global_load_lds_dwordx4 v146, s[56:57]
	s_add_u32 s56, s56, 0x100000
	s_addc_u32 s57, s57, 0
	s_add_i32 s91, s78, s63
	s_mov_b32 m0, s91
	s_nop 0
	global_load_lds_dwordx4 v142, s[56:57]
	s_add_i32 m0, s91, 0x2000
	s_nop 0
	global_load_lds_dwordx4 v146, s[56:57]
	s_mov_b32 m0, s64
	s_nop 0
	global_load_lds_dwordx4 v140, s[42:43]
	s_mov_b32 m0, s65
	s_nop 0
	global_load_lds_dwordx4 v144, s[42:43]
	s_waitcnt vmcnt(8)
	s_waitcnt lgkmcnt(0)
	s_setprio 1
	s_barrier
	v_mfma_f32_16x16x32_bf16 v[64:67], v[132:135], v[188:191], 0
	v_mfma_f32_16x16x32_bf16 v[60:63], v[156:159], v[188:191], 0
	v_mfma_f32_16x16x32_bf16 v[56:59], v[132:135], v[196:199], 0
	v_mfma_f32_16x16x32_bf16 v[52:55], v[156:159], v[196:199], 0
	v_mfma_f32_16x16x32_bf16 v[48:51], v[132:135], v[204:207], 0
	v_mfma_f32_16x16x32_bf16 v[44:47], v[156:159], v[204:207], 0
	v_mfma_f32_16x16x32_bf16 v[40:43], v[132:135], v[212:215], 0
	v_mfma_f32_16x16x32_bf16 v[36:39], v[156:159], v[212:215], 0
	v_mfma_f32_16x16x32_bf16 v[64:67], v[136:139], v[192:195], v[64:67]
	v_mfma_f32_16x16x32_bf16 v[60:63], v[160:163], v[192:195], v[60:63]
	v_mfma_f32_16x16x32_bf16 v[56:59], v[136:139], v[200:203], v[56:59]
	v_mfma_f32_16x16x32_bf16 v[52:55], v[160:163], v[200:203], v[52:55]
	v_mfma_f32_16x16x32_bf16 v[48:51], v[136:139], v[208:211], v[48:51]
	v_mfma_f32_16x16x32_bf16 v[44:47], v[160:163], v[208:211], v[44:47]
	v_mfma_f32_16x16x32_bf16 v[40:43], v[136:139], v[216:219], v[40:43]
	v_mfma_f32_16x16x32_bf16 v[36:39], v[160:163], v[216:219], v[36:39]
	v_mfma_f32_16x16x32_bf16 v[32:35], v[172:175], v[188:191], 0
	v_mfma_f32_16x16x32_bf16 v[28:31], v[180:183], v[188:191], 0
	v_mfma_f32_16x16x32_bf16 v[24:27], v[172:175], v[196:199], 0
	v_mfma_f32_16x16x32_bf16 v[20:23], v[180:183], v[196:199], 0
	v_mfma_f32_16x16x32_bf16 v[16:19], v[172:175], v[204:207], 0
	v_mfma_f32_16x16x32_bf16 v[12:15], v[180:183], v[204:207], 0
	v_mfma_f32_16x16x32_bf16 v[8:11], v[172:175], v[212:215], 0
	v_mfma_f32_16x16x32_bf16 v[2:5], v[180:183], v[212:215], 0
	v_mfma_f32_16x16x32_bf16 v[32:35], v[176:179], v[192:195], v[32:35]
	v_mfma_f32_16x16x32_bf16 v[28:31], v[184:187], v[192:195], v[28:31]
	v_mfma_f32_16x16x32_bf16 v[24:27], v[176:179], v[200:203], v[24:27]
	v_mfma_f32_16x16x32_bf16 v[20:23], v[184:187], v[200:203], v[20:23]
	v_mfma_f32_16x16x32_bf16 v[16:19], v[176:179], v[208:211], v[16:19]
	v_mfma_f32_16x16x32_bf16 v[12:15], v[184:187], v[208:211], v[12:15]
	v_mfma_f32_16x16x32_bf16 v[8:11], v[176:179], v[216:219], v[8:11]
	v_mfma_f32_16x16x32_bf16 v[2:5], v[184:187], v[216:219], v[2:5]
	s_barrier
	s_branch .Lmid_k966
	.p2align	6

; #define PG8_STAGE(bufoff, gbase, voff) do { _Pragma("unroll") for (int _i = 0; _i < 2; ++_i) \
;         __builtin_amdgcn_global_load_lds((const unsigned*)((const char*)(gbase) + (voff)[_i]), (PG8_LAS unsigned*)(lds + (bufoff) + ldsw + _i * 8192), 16, 0, 0); } while (0)
; #define PG8_LDA(dst, b, h) do { _Pragma("unroll") for (int m = 0; m < 4; ++m) _Pragma("unroll") for (int k = 0; k < 2; ++k) dst[m][k] = *(const PG8_LAS bf16x8*)(lds + PG8_SA(b, h) + aoff + m * 2048 + k * 1024); } while (0)
; #define PG8_LDB(dst, b, h) do { _Pragma("unroll") for (int n = 0; n < 2; ++n) _Pragma("unroll") for (int k = 0; k < 2; ++k) dst[n][k] = *(const PG8_LAS bf16x8*)(lds + PG8_SB(b, h) + boff + n * 2048 + k * 1024); } while (0)
; #define PG8_WAIT_V(n) asm volatile("s_waitcnt vmcnt(" #n ")" ::: "memory")
; #define PG8_WAIT_L(n) asm volatile("s_waitcnt lgkmcnt(" #n ")" ::: "memory")
; #define PG8_BAR __builtin_amdgcn_s_barrier()
; template <class Epi, class Sched, bool ALIGN_EPI = false, bool SP2 = false, bool F8 = false>
; __device__ __forceinline__ void gemm_phase(PG8_LAS unsigned char* lds, const int K, const Sched& S, const Epi& E, const int wave) {
;     ...
;             const bool last = (t == nt - 2);
;             const char* a1 = cA + (size_t)(t + 1) * kstep;
;             const char* a2 = last ? nA : cA + (size_t)(t + 2) * kstep; const char* b2 = last ? nB : cB + (size_t)(t + 2) * kstep;
;             const char* a3 = a2 + kstep; const char* b3 = b2 + kstep;
;             asm volatile("" : "+s"(a1), "+s"(a2), "+s"(b2), "+s"(a3), "+s"(b3));
;             if (last && has_next) S.a_ready(nxt);
;             if constexpr (Epi::KHOOK) { if (cur.prob == 2 ? (t == 16) : (t == 32 || t == 48)) { if (wr == 0) PG8_BAR;
;                 E.khook(acc, cur, (cur.prob == 2 || t == 48) ? 1 : 0, wr, wc, fr, fq); if (wr == 1) PG8_BAR; } }
;             if constexpr (SP2) {
;             PG8_LDB(B0, 0, 0); PG8_LDB(B1, 0, 1); PG8_SCHED; PG8_LDA(At, 0, 0); PG8_STAGE(PG8_SA(1, 1), a1 + hstep, voffA);
;             PG8_WAIT_V(8); PG8_WAIT_L(0); PG8_BAR; PG8_MMA(0, 0, At, B0); PG8_MMA(0, 1, At, B1); PG8_BAR; PG8_SCHED;
;             PG8_LDA(At, 0, 1); PG8_STAGE(PG8_SB(0, 0), b2, voffB); PG8_STAGE(PG8_SB(0, 1), b2 + hstep, voffB); PG8_STAGE(PG8_SA(0, 0), a2, voffA);
;             PG8_WAIT_V(8); PG8_WAIT_L(0); PG8_BAR; PG8_MMA(1, 0, At, B0); PG8_MMA(1, 1, At, B1); PG8_BAR; PG8_SCHED;
.Lpeel_k1240:
	s_add_u32 s25, s10, s38
	s_addc_u32 s40, s11, s39
	s_add_u32 s64, s25, 0xffffff80
	s_addc_u32 s65, s40, -1
	s_add_u32 s41, s12, s38
	s_addc_u32 s42, s13, s39
	s_cmp_eq_u32 s23, 60
	s_cselect_b32 s44, s30, s25
	s_cselect_b32 s45, s31, s40
	s_cselect_b32 s53, s37, s42
	s_cselect_b32 s52, s36, s41
	s_add_u32 s40, s44, 0x80
	s_addc_u32 s41, s45, 0
	s_add_u32 s42, s52, 0x80
	s_addc_u32 s43, s53, 0
	v_add_u32_e32 v149, s59, v146
	ds_read_b128 v[140:143], v149
	ds_read_b128 v[150:153], v149 offset:1024
	ds_read_b128 v[154:157], v149 offset:2048
	ds_read_b128 v[158:161], v149 offset:3072
	v_add_u32_e32 v149, s60, v146
	ds_read_b128 v[162:165], v149
	ds_read_b128 v[166:169], v149 offset:1024
	ds_read_b128 v[170:173], v149 offset:2048
	ds_read_b128 v[174:177], v149 offset:3072
	s_add_u32 s64, s64, 0x100000
	s_addc_u32 s65, s65, 0
	s_add_i32 m0, s9, 0xc000
	ds_read_b128 v[178:181], v148
	ds_read_b128 v[182:185], v148 offset:1024
	ds_read_b128 v[186:189], v148 offset:2048
	ds_read_b128 v[190:193], v148 offset:3072
	ds_read_b128 v[194:197], v148 offset:4096
	ds_read_b128 v[198:201], v148 offset:5120
	ds_read_b128 v[202:205], v148 offset:6144
	ds_read_b128 v[206:209], v148 offset:7168
	global_load_lds_dwordx4 v134, s[64:65]
	s_add_i32 m0, s9, 0xe000
	s_nop 0
	global_load_lds_dwordx4 v130, s[64:65]
	s_waitcnt vmcnt(8)
	s_waitcnt lgkmcnt(0)
	s_setprio 1
	s_barrier
	v_mfma_f32_16x16x32_bf16 v[124:127], v[140:143], v[178:181], 0
	v_mfma_f32_16x16x32_bf16 v[120:123], v[154:157], v[178:181], 0
	v_mfma_f32_16x16x32_bf16 v[116:119], v[140:143], v[186:189], 0
	v_mfma_f32_16x16x32_bf16 v[112:115], v[154:157], v[186:189], 0
	v_mfma_f32_16x16x32_bf16 v[108:111], v[140:143], v[194:197], 0
	v_mfma_f32_16x16x32_bf16 v[104:107], v[154:157], v[194:197], 0
	v_mfma_f32_16x16x32_bf16 v[100:103], v[140:143], v[202:205], 0
	v_mfma_f32_16x16x32_bf16 v[96:99], v[154:157], v[202:205], 0
	v_mfma_f32_16x16x32_bf16 v[124:127], v[150:153], v[182:185], v[124:127]
	v_mfma_f32_16x16x32_bf16 v[120:123], v[158:161], v[182:185], v[120:123]
	v_mfma_f32_16x16x32_bf16 v[116:119], v[150:153], v[190:193], v[116:119]
	v_mfma_f32_16x16x32_bf16 v[112:115], v[158:161], v[190:193], v[112:115]
	v_mfma_f32_16x16x32_bf16 v[108:111], v[150:153], v[198:201], v[108:111]
	v_mfma_f32_16x16x32_bf16 v[104:107], v[158:161], v[198:201], v[104:107]
	v_mfma_f32_16x16x32_bf16 v[100:103], v[150:153], v[206:209], v[100:103]
	v_mfma_f32_16x16x32_bf16 v[96:99], v[158:161], v[206:209], v[96:99]
	v_mfma_f32_16x16x32_bf16 v[92:95], v[162:165], v[178:181], 0
	v_mfma_f32_16x16x32_bf16 v[88:91], v[170:173], v[178:181], 0
	v_mfma_f32_16x16x32_bf16 v[84:87], v[162:165], v[186:189], 0
	v_mfma_f32_16x16x32_bf16 v[80:83], v[170:173], v[186:189], 0
	v_mfma_f32_16x16x32_bf16 v[76:79], v[162:165], v[194:197], 0
	v_mfma_f32_16x16x32_bf16 v[72:75], v[170:173], v[194:197], 0
	v_mfma_f32_16x16x32_bf16 v[68:71], v[162:165], v[202:205], 0
	v_mfma_f32_16x16x32_bf16 v[64:67], v[170:173], v[202:205], 0
	v_mfma_f32_16x16x32_bf16 v[92:95], v[166:169], v[182:185], v[92:95]
	v_mfma_f32_16x16x32_bf16 v[88:91], v[174:177], v[182:185], v[88:91]
	v_mfma_f32_16x16x32_bf16 v[84:87], v[166:169], v[190:193], v[84:87]
	v_mfma_f32_16x16x32_bf16 v[80:83], v[174:177], v[190:193], v[80:83]
	v_mfma_f32_16x16x32_bf16 v[76:79], v[166:169], v[198:201], v[76:79]
	v_mfma_f32_16x16x32_bf16 v[72:75], v[174:177], v[198:201], v[72:75]
	v_mfma_f32_16x16x32_bf16 v[68:71], v[166:169], v[206:209], v[68:71]
	v_mfma_f32_16x16x32_bf16 v[64:67], v[174:177], v[206:209], v[64:67]
	s_barrier
	s_setprio 0
	s_add_i32 s25, s59, s48
	s_mov_b32 m0, s25
	ds_read_b128 v[178:181], v148 offset:16384
	ds_read_b128 v[182:185], v148 offset:17408
	ds_read_b128 v[186:189], v148 offset:18432
	ds_read_b128 v[190:193], v148 offset:19456
	ds_read_b128 v[194:197], v148 offset:20480
	ds_read_b128 v[198:201], v148 offset:21504
	ds_read_b128 v[202:205], v148 offset:22528
	ds_read_b128 v[206:209], v148 offset:23552
	global_load_lds_dwordx4 v132, s[52:53]
	s_add_i32 m0, s25, 0x2000
	s_nop 0
	global_load_lds_dwordx4 v128, s[52:53]
	s_add_u32 s52, s52, 0x100000
	s_addc_u32 s53, s53, 0
	s_add_i32 s25, s60, s48
	s_mov_b32 m0, s25
	s_nop 0
	global_load_lds_dwordx4 v132, s[52:53]
	s_add_i32 m0, s25, 0x2000
	s_nop 0
	global_load_lds_dwordx4 v128, s[52:53]
	s_mov_b32 m0, s9
	s_nop 0
	global_load_lds_dwordx4 v134, s[44:45]
	s_mov_b32 m0, s50
	s_nop 0
	global_load_lds_dwordx4 v130, s[44:45]
	s_waitcnt vmcnt(8)
	s_waitcnt lgkmcnt(0)
	s_setprio 1
	s_barrier
	v_mfma_f32_16x16x32_bf16 v[60:63], v[140:143], v[178:181], 0
	v_mfma_f32_16x16x32_bf16 v[56:59], v[154:157], v[178:181], 0
	v_mfma_f32_16x16x32_bf16 v[52:55], v[140:143], v[186:189], 0
	v_mfma_f32_16x16x32_bf16 v[48:51], v[154:157], v[186:189], 0
	v_mfma_f32_16x16x32_bf16 v[44:47], v[140:143], v[194:197], 0
	v_mfma_f32_16x16x32_bf16 v[40:43], v[154:157], v[194:197], 0
	v_mfma_f32_16x16x32_bf16 v[36:39], v[140:143], v[202:205], 0
	v_mfma_f32_16x16x32_bf16 v[32:35], v[154:157], v[202:205], 0
	v_mfma_f32_16x16x32_bf16 v[60:63], v[150:153], v[182:185], v[60:63]
	v_mfma_f32_16x16x32_bf16 v[56:59], v[158:161], v[182:185], v[56:59]
	v_mfma_f32_16x16x32_bf16 v[52:55], v[150:153], v[190:193], v[52:55]
	v_mfma_f32_16x16x32_bf16 v[48:51], v[158:161], v[190:193], v[48:51]
	v_mfma_f32_16x16x32_bf16 v[44:47], v[150:153], v[198:201], v[44:47]
	v_mfma_f32_16x16x32_bf16 v[40:43], v[158:161], v[198:201], v[40:43]
	v_mfma_f32_16x16x32_bf16 v[36:39], v[150:153], v[206:209], v[36:39]
	v_mfma_f32_16x16x32_bf16 v[32:35], v[158:161], v[206:209], v[32:35]
	v_mfma_f32_16x16x32_bf16 v[28:31], v[162:165], v[178:181], 0
	v_mfma_f32_16x16x32_bf16 v[24:27], v[170:173], v[178:181], 0
	v_mfma_f32_16x16x32_bf16 v[20:23], v[162:165], v[186:189], 0
	v_mfma_f32_16x16x32_bf16 v[16:19], v[170:173], v[186:189], 0
	v_mfma_f32_16x16x32_bf16 v[12:15], v[162:165], v[194:197], 0
	v_mfma_f32_16x16x32_bf16 v[8:11], v[170:173], v[194:197], 0
	v_mfma_f32_16x16x32_bf16 v[4:7], v[162:165], v[202:205], 0
	v_mfma_f32_16x16x32_bf16 v[0:3], v[170:173], v[202:205], 0
	v_mfma_f32_16x16x32_bf16 v[28:31], v[166:169], v[182:185], v[28:31]
	v_mfma_f32_16x16x32_bf16 v[24:27], v[174:177], v[182:185], v[24:27]
	v_mfma_f32_16x16x32_bf16 v[20:23], v[166:169], v[190:193], v[20:23]
	v_mfma_f32_16x16x32_bf16 v[16:19], v[174:177], v[190:193], v[16:19]
	v_mfma_f32_16x16x32_bf16 v[12:15], v[166:169], v[198:201], v[12:15]
	v_mfma_f32_16x16x32_bf16 v[8:11], v[174:177], v[198:201], v[8:11]
	v_mfma_f32_16x16x32_bf16 v[4:7], v[166:169], v[206:209], v[4:7]
	v_mfma_f32_16x16x32_bf16 v[0:3], v[174:177], v[206:209], v[0:3]
	s_barrier
	s_branch .Lmid_k1240
	.p2align	6

; #define PG8_STAGE(bufoff, gbase, voff) do { _Pragma("unroll") for (int _i = 0; _i < 2; ++_i) \
;         __builtin_amdgcn_global_load_lds((const unsigned*)((const char*)(gbase) + (voff)[_i]), (PG8_LAS unsigned*)(lds + (bufoff) + ldsw + _i * 8192), 16, 0, 0); } while (0)
; #define PG8_LDA(dst, b, h) do { _Pragma("unroll") for (int m = 0; m < 4; ++m) _Pragma("unroll") for (int k = 0; k < 2; ++k) dst[m][k] = *(const PG8_LAS bf16x8*)(lds + PG8_SA(b, h) + aoff + m * 2048 + k * 1024); } while (0)
; #define PG8_LDB(dst, b, h) do { _Pragma("unroll") for (int n = 0; n < 2; ++n) _Pragma("unroll") for (int k = 0; k < 2; ++k) dst[n][k] = *(const PG8_LAS bf16x8*)(lds + PG8_SB(b, h) + boff + n * 2048 + k * 1024); } while (0)
; #define PG8_WAIT_V(n) asm volatile("s_waitcnt vmcnt(" #n ")" ::: "memory")
; #define PG8_WAIT_L(n) asm volatile("s_waitcnt lgkmcnt(" #n ")" ::: "memory")
; #define PG8_BAR __builtin_amdgcn_s_barrier()
; template <class Epi, class Sched, bool ALIGN_EPI = false, bool SP2 = false, bool F8 = false>
; __device__ __forceinline__ void gemm_phase(PG8_LAS unsigned char* lds, const int K, const Sched& S, const Epi& E, const int wave) {
;     ...
;             const bool last = (t == nt - 2);
;             const char* a1 = cA + (size_t)(t + 1) * kstep;
;             const char* a2 = last ? nA : cA + (size_t)(t + 2) * kstep; const char* b2 = last ? nB : cB + (size_t)(t + 2) * kstep;
;             const char* a3 = a2 + kstep; const char* b3 = b2 + kstep;
;             asm volatile("" : "+s"(a1), "+s"(a2), "+s"(b2), "+s"(a3), "+s"(b3));
;             if (last && has_next) S.a_ready(nxt);
;             if constexpr (Epi::KHOOK) { if (cur.prob == 2 ? (t == 16) : (t == 32 || t == 48)) { if (wr == 0) PG8_BAR;
;                 E.khook(acc, cur, (cur.prob == 2 || t == 48) ? 1 : 0, wr, wc, fr, fq); if (wr == 1) PG8_BAR; } }
;             if constexpr (SP2) {
;             PG8_LDB(B0, 0, 0); PG8_LDB(B1, 0, 1); PG8_SCHED; PG8_LDA(At, 0, 0); PG8_STAGE(PG8_SA(1, 1), a1 + hstep, voffA);
;             PG8_WAIT_V(8); PG8_WAIT_L(0); PG8_BAR; PG8_MMA(0, 0, At, B0); PG8_MMA(0, 1, At, B1); PG8_BAR; PG8_SCHED;
;             PG8_LDA(At, 0, 1); PG8_STAGE(PG8_SB(0, 0), b2, voffB); PG8_STAGE(PG8_SB(0, 1), b2 + hstep, voffB); PG8_STAGE(PG8_SA(0, 0), a2, voffA);
;             PG8_WAIT_V(8); PG8_WAIT_L(0); PG8_BAR; PG8_MMA(1, 0, At, B0); PG8_MMA(1, 1, At, B1); PG8_BAR; PG8_SCHED;
.Lpeel_k1348:
	s_add_i32 s87, s8, 2
	s_cmp_eq_u32 s82, s8
	s_cselect_b32 s40, s79, s83
	s_cselect_b32 s41, s78, s84
	s_cselect_b32 s43, s80, s86
	s_cselect_b32 s42, s81, s85
	s_add_u32 s8, s40, 0x80
	s_addc_u32 s9, s41, 0
	s_add_u32 s38, s42, 0x80
	s_addc_u32 s39, s43, 0
	s_mov_b64 s[88:89], s[6:7]
	v_add_u32_e32 v1, s67, v166
	ds_read_b128 v[132:135], v1
	ds_read_b128 v[136:139], v1 offset:1024
	ds_read_b128 v[156:159], v1 offset:2048
	ds_read_b128 v[160:163], v1 offset:3072
	v_add_u32_e32 v1, s72, v166
	ds_read_b128 v[170:173], v1
	ds_read_b128 v[174:177], v1 offset:1024
	ds_read_b128 v[178:181], v1 offset:2048
	ds_read_b128 v[182:185], v1 offset:3072
	s_add_u32 s88, s88, 0x2b0000
	s_addc_u32 s89, s89, 0
	s_add_i32 m0, s58, 0xc000
	ds_read_b128 v[186:189], v168
	ds_read_b128 v[190:193], v168 offset:1024
	ds_read_b128 v[194:197], v168 offset:2048
	ds_read_b128 v[198:201], v168 offset:3072
	ds_read_b128 v[202:205], v168 offset:4096
	ds_read_b128 v[206:209], v168 offset:5120
	ds_read_b128 v[210:213], v168 offset:6144
	ds_read_b128 v[214:217], v168 offset:7168
	global_load_lds_dwordx4 v140, s[88:89]
	s_add_i32 m0, s58, 0xe000
	s_nop 0
	global_load_lds_dwordx4 v144, s[88:89]
	s_waitcnt vmcnt(8)
	s_waitcnt lgkmcnt(0)
	s_setprio 1
	s_barrier
	v_mfma_f32_16x16x32_bf16 v[128:131], v[132:135], v[186:189], 0
	v_mfma_f32_16x16x32_bf16 v[124:127], v[156:159], v[186:189], 0
	v_mfma_f32_16x16x32_bf16 v[120:123], v[132:135], v[194:197], 0
	v_mfma_f32_16x16x32_bf16 v[116:119], v[156:159], v[194:197], 0
	v_mfma_f32_16x16x32_bf16 v[112:115], v[132:135], v[202:205], 0
	v_mfma_f32_16x16x32_bf16 v[108:111], v[156:159], v[202:205], 0
	v_mfma_f32_16x16x32_bf16 v[104:107], v[132:135], v[210:213], 0
	v_mfma_f32_16x16x32_bf16 v[100:103], v[156:159], v[210:213], 0
	v_mfma_f32_16x16x32_bf16 v[128:131], v[136:139], v[190:193], v[128:131]
	v_mfma_f32_16x16x32_bf16 v[124:127], v[160:163], v[190:193], v[124:127]
	v_mfma_f32_16x16x32_bf16 v[120:123], v[136:139], v[198:201], v[120:123]
	v_mfma_f32_16x16x32_bf16 v[116:119], v[160:163], v[198:201], v[116:119]
	v_mfma_f32_16x16x32_bf16 v[112:115], v[136:139], v[206:209], v[112:115]
	v_mfma_f32_16x16x32_bf16 v[108:111], v[160:163], v[206:209], v[108:111]
	v_mfma_f32_16x16x32_bf16 v[104:107], v[136:139], v[214:217], v[104:107]
	v_mfma_f32_16x16x32_bf16 v[100:103], v[160:163], v[214:217], v[100:103]
	v_mfma_f32_16x16x32_bf16 v[96:99], v[170:173], v[186:189], 0
	v_mfma_f32_16x16x32_bf16 v[92:95], v[178:181], v[186:189], 0
	v_mfma_f32_16x16x32_bf16 v[88:91], v[170:173], v[194:197], 0
	v_mfma_f32_16x16x32_bf16 v[84:87], v[178:181], v[194:197], 0
	v_mfma_f32_16x16x32_bf16 v[80:83], v[170:173], v[202:205], 0
	v_mfma_f32_16x16x32_bf16 v[76:79], v[178:181], v[202:205], 0
	v_mfma_f32_16x16x32_bf16 v[72:75], v[170:173], v[210:213], 0
	v_mfma_f32_16x16x32_bf16 v[68:71], v[178:181], v[210:213], 0
	v_mfma_f32_16x16x32_bf16 v[96:99], v[174:177], v[190:193], v[96:99]
	v_mfma_f32_16x16x32_bf16 v[92:95], v[182:185], v[190:193], v[92:95]
	v_mfma_f32_16x16x32_bf16 v[88:91], v[174:177], v[198:201], v[88:91]
	v_mfma_f32_16x16x32_bf16 v[84:87], v[182:185], v[198:201], v[84:87]
	v_mfma_f32_16x16x32_bf16 v[80:83], v[174:177], v[206:209], v[80:83]
	v_mfma_f32_16x16x32_bf16 v[76:79], v[182:185], v[206:209], v[76:79]
	v_mfma_f32_16x16x32_bf16 v[72:75], v[174:177], v[214:217], v[72:75]
	v_mfma_f32_16x16x32_bf16 v[68:71], v[182:185], v[214:217], v[68:71]
	s_barrier
	s_setprio 0
	s_add_i32 s88, s67, s57
	s_mov_b32 m0, s88
	ds_read_b128 v[186:189], v168 offset:16384
	ds_read_b128 v[190:193], v168 offset:17408
	ds_read_b128 v[194:197], v168 offset:18432
	ds_read_b128 v[198:201], v168 offset:19456
	ds_read_b128 v[202:205], v168 offset:20480
	ds_read_b128 v[206:209], v168 offset:21504
	ds_read_b128 v[210:213], v168 offset:22528
	ds_read_b128 v[214:217], v168 offset:23552
	global_load_lds_dwordx4 v142, s[42:43]
	s_add_i32 m0, s88, 0x2000
	s_nop 0
	global_load_lds_dwordx4 v146, s[42:43]
	s_add_u32 s42, s42, 0x2b0000
	s_addc_u32 s43, s43, 0
	s_add_i32 s88, s72, s57
	s_mov_b32 m0, s88
	s_nop 0
	global_load_lds_dwordx4 v142, s[42:43]
	s_add_i32 m0, s88, 0x2000
	s_nop 0
	global_load_lds_dwordx4 v146, s[42:43]
	s_mov_b32 m0, s58
	s_nop 0
	global_load_lds_dwordx4 v140, s[40:41]
	s_mov_b32 m0, s59
	s_nop 0
	global_load_lds_dwordx4 v144, s[40:41]
	s_waitcnt vmcnt(8)
	s_waitcnt lgkmcnt(0)
	s_setprio 1
	s_barrier
	v_mfma_f32_16x16x32_bf16 v[64:67], v[132:135], v[186:189], 0
	v_mfma_f32_16x16x32_bf16 v[60:63], v[156:159], v[186:189], 0
	v_mfma_f32_16x16x32_bf16 v[56:59], v[132:135], v[194:197], 0
	v_mfma_f32_16x16x32_bf16 v[52:55], v[156:159], v[194:197], 0
	v_mfma_f32_16x16x32_bf16 v[48:51], v[132:135], v[202:205], 0
	v_mfma_f32_16x16x32_bf16 v[44:47], v[156:159], v[202:205], 0
	v_mfma_f32_16x16x32_bf16 v[40:43], v[132:135], v[210:213], 0
	v_mfma_f32_16x16x32_bf16 v[36:39], v[156:159], v[210:213], 0
	v_mfma_f32_16x16x32_bf16 v[64:67], v[136:139], v[190:193], v[64:67]
	v_mfma_f32_16x16x32_bf16 v[60:63], v[160:163], v[190:193], v[60:63]
	v_mfma_f32_16x16x32_bf16 v[56:59], v[136:139], v[198:201], v[56:59]
	v_mfma_f32_16x16x32_bf16 v[52:55], v[160:163], v[198:201], v[52:55]
	v_mfma_f32_16x16x32_bf16 v[48:51], v[136:139], v[206:209], v[48:51]
	v_mfma_f32_16x16x32_bf16 v[44:47], v[160:163], v[206:209], v[44:47]
	v_mfma_f32_16x16x32_bf16 v[40:43], v[136:139], v[214:217], v[40:43]
	v_mfma_f32_16x16x32_bf16 v[36:39], v[160:163], v[214:217], v[36:39]
	v_mfma_f32_16x16x32_bf16 v[32:35], v[170:173], v[186:189], 0
	v_mfma_f32_16x16x32_bf16 v[28:31], v[178:181], v[186:189], 0
	v_mfma_f32_16x16x32_bf16 v[24:27], v[170:173], v[194:197], 0
	v_mfma_f32_16x16x32_bf16 v[20:23], v[178:181], v[194:197], 0
	v_mfma_f32_16x16x32_bf16 v[16:19], v[170:173], v[202:205], 0
	v_mfma_f32_16x16x32_bf16 v[12:15], v[178:181], v[202:205], 0
	v_mfma_f32_16x16x32_bf16 v[8:11], v[170:173], v[210:213], 0
	v_mfma_f32_16x16x32_bf16 v[2:5], v[178:181], v[210:213], 0
	v_mfma_f32_16x16x32_bf16 v[32:35], v[174:177], v[190:193], v[32:35]
	v_mfma_f32_16x16x32_bf16 v[28:31], v[182:185], v[190:193], v[28:31]
	v_mfma_f32_16x16x32_bf16 v[24:27], v[174:177], v[198:201], v[24:27]
	v_mfma_f32_16x16x32_bf16 v[20:23], v[182:185], v[198:201], v[20:23]
	v_mfma_f32_16x16x32_bf16 v[16:19], v[174:177], v[206:209], v[16:19]
	v_mfma_f32_16x16x32_bf16 v[12:15], v[182:185], v[206:209], v[12:15]
	v_mfma_f32_16x16x32_bf16 v[8:11], v[174:177], v[214:217], v[8:11]
	v_mfma_f32_16x16x32_bf16 v[2:5], v[182:185], v[214:217], v[2:5]
	s_barrier
	s_branch .Lmid_k1348
	.p2align	6
